# hot-loop placement: heads of the seven GEMM K-loops and the two mixer C tile loops aligned to 64 bytes (s_nop fill executed once per loop entry)
# baseline (speedup 1.0000x reference)
; template <class Epi, class Sched, bool ALIGN_EPI = false, bool SP2 = false>
; __device__ __forceinline__ void gemm_phase(PG8_LAS unsigned char* lds, const Gemm g, const Sched& S, const Epi& E, int wave_s) {
;     ...
;         const bool has_next = S.next(ui + 1, nxt);
;         const char* nA = has_next ? (const char*)g.A + (size_t)nxt.pm * tstep : cA; const char* nB = has_next ? (const char*)g.Bt + (size_t)nxt.pn * tstep : cB;
;         for (int t = 0; t < nt; t += 2) {
;             const bool last = (t == nt - 2);
;             const char* a1 = cA + (size_t)(t + 1) * kstep;
;             const char* a2 = last ? nA : cA + (size_t)(t + 2) * kstep; const char* b2 = last ? nB : cB + (size_t)(t + 2) * kstep;
;             const char* a3 = a2 + kstep; const char* b3 = b2 + kstep;
;     ...
; #pragma unroll
;         for (int a = 0; a < 2; ++a)
; #pragma unroll
;             for (int b = 0; b < 2; ++b)
; #pragma unroll
;                 for (int m = 0; m < 4; ++m)
; #pragma unroll
;                     for (int n = 0; n < 2; ++n) acc[a][b][m][n] = (f32x4){0.f, 0.f, 0.f, 0.f};
.LBB0_222:
	s_ashr_i32 s89, s88, 31
	s_lshl_b64 s[12:13], s[88:89], 19
	s_add_u32 s90, s37, s12
	s_addc_u32 s91, s38, s13
	s_and_b64 s[12:13], s[0:1], exec
	s_cselect_b32 s8, s91, s25
	s_cselect_b32 s12, s90, s24
	s_ashr_i32 s63, s62, 31
	s_lshl_b64 s[28:29], s[62:63], 19
	s_add_u32 s92, s39, s28
	s_addc_u32 s93, s40, s29
	s_and_b64 s[28:29], s[0:1], exec
	s_cselect_b32 s13, s93, s27
	s_cselect_b32 s18, s92, s26
	s_add_u32 s24, s24, 0x40080
	s_addc_u32 s25, s25, 0
	s_add_u32 s23, s26, 0x100
	v_mov_b32_e32 v2, 0
	s_addc_u32 s30, s27, 0
	s_mov_b32 s31, -2
	v_mov_b32_e32 v3, v2
	v_mov_b64_e32 v[4:5], v[2:3]
	v_mov_b64_e32 v[6:7], v[2:3]
	v_mov_b64_e32 v[8:9], v[2:3]
	v_mov_b64_e32 v[10:11], v[2:3]
	v_mov_b64_e32 v[12:13], v[2:3]
	v_mov_b64_e32 v[14:15], v[2:3]
	v_mov_b64_e32 v[16:17], v[2:3]
	v_mov_b64_e32 v[18:19], v[2:3]
	v_mov_b64_e32 v[20:21], v[2:3]
	v_mov_b64_e32 v[22:23], v[2:3]
	v_mov_b64_e32 v[24:25], v[2:3]
	v_mov_b64_e32 v[26:27], v[2:3]
	v_mov_b64_e32 v[28:29], v[2:3]
	v_mov_b64_e32 v[30:31], v[2:3]
	v_mov_b64_e32 v[32:33], v[2:3]
	v_mov_b64_e32 v[34:35], v[2:3]
	v_mov_b64_e32 v[36:37], v[2:3]
	v_mov_b64_e32 v[38:39], v[2:3]
	v_mov_b64_e32 v[40:41], v[2:3]
	v_mov_b64_e32 v[42:43], v[2:3]
	v_mov_b64_e32 v[44:45], v[2:3]
	v_mov_b64_e32 v[46:47], v[2:3]
	v_mov_b64_e32 v[48:49], v[2:3]
	v_mov_b64_e32 v[50:51], v[2:3]
	v_mov_b64_e32 v[52:53], v[2:3]
	v_mov_b64_e32 v[54:55], v[2:3]
	v_mov_b64_e32 v[56:57], v[2:3]
	v_mov_b64_e32 v[58:59], v[2:3]
	v_mov_b64_e32 v[60:61], v[2:3]
	v_mov_b64_e32 v[62:63], v[2:3]
	v_mov_b64_e32 v[64:65], v[2:3]
	v_mov_b64_e32 v[66:67], v[2:3]
	v_mov_b64_e32 v[68:69], v[2:3]
	v_mov_b64_e32 v[70:71], v[2:3]
	v_mov_b64_e32 v[72:73], v[2:3]
	v_mov_b64_e32 v[74:75], v[2:3]
	v_mov_b64_e32 v[76:77], v[2:3]
	v_mov_b64_e32 v[78:79], v[2:3]
	v_mov_b64_e32 v[80:81], v[2:3]
	v_mov_b64_e32 v[82:83], v[2:3]
	v_mov_b64_e32 v[84:85], v[2:3]
	v_mov_b64_e32 v[86:87], v[2:3]
	v_mov_b64_e32 v[88:89], v[2:3]
	v_mov_b64_e32 v[90:91], v[2:3]
	v_mov_b64_e32 v[92:93], v[2:3]
	v_mov_b64_e32 v[94:95], v[2:3]
	v_mov_b64_e32 v[96:97], v[2:3]
	v_mov_b64_e32 v[98:99], v[2:3]
	v_mov_b64_e32 v[100:101], v[2:3]
	v_mov_b64_e32 v[102:103], v[2:3]
	v_mov_b64_e32 v[104:105], v[2:3]
	v_mov_b64_e32 v[106:107], v[2:3]
	v_mov_b64_e32 v[108:109], v[2:3]
	v_mov_b64_e32 v[110:111], v[2:3]
	v_mov_b64_e32 v[112:113], v[2:3]
	v_mov_b64_e32 v[114:115], v[2:3]
	v_mov_b64_e32 v[116:117], v[2:3]
	v_mov_b64_e32 v[118:119], v[2:3]
	v_mov_b64_e32 v[120:121], v[2:3]
	v_mov_b64_e32 v[122:123], v[2:3]
	v_mov_b64_e32 v[124:125], v[2:3]
	v_mov_b64_e32 v[126:127], v[2:3]
	v_mov_b64_e32 v[128:129], v[2:3]
	.p2alignl 6, 3212836864

; template <class Epi, class Sched, bool ALIGN_EPI = false, bool SP2 = false>
; __device__ __forceinline__ void gemm_phase(PG8_LAS unsigned char* lds, const Gemm g, const Sched& S, const Epi& E, int wave_s) {
;     ...
;         const bool has_next = S.next(ui + 1, nxt);
;         const char* nA = has_next ? (const char*)g.A + (size_t)nxt.pm * tstep : cA; const char* nB = has_next ? (const char*)g.Bt + (size_t)nxt.pn * tstep : cB;
;         for (int t = 0; t < nt; t += 2) {
;             const bool last = (t == nt - 2);
;             const char* a1 = cA + (size_t)(t + 1) * kstep;
;             const char* a2 = last ? nA : cA + (size_t)(t + 2) * kstep; const char* b2 = last ? nB : cB + (size_t)(t + 2) * kstep;
;             const char* a3 = a2 + kstep; const char* b3 = b2 + kstep;
;     ...
; #pragma unroll
;         for (int a = 0; a < 2; ++a)
; #pragma unroll
;             for (int b = 0; b < 2; ++b)
; #pragma unroll
;                 for (int m = 0; m < 4; ++m)
; #pragma unroll
;                     for (int n = 0; n < 2; ++n) acc[a][b][m][n] = (f32x4){0.f, 0.f, 0.f, 0.f};
.LBB0_256:
	s_ashr_i32 s93, s92, 31
	s_lshl_b64 s[28:29], s[92:93], 19
	s_add_u32 s94, s13, s28
	s_addc_u32 s95, s16, s29
	s_and_b64 s[28:29], s[0:1], exec
	s_cselect_b32 s30, s95, s25
	s_cselect_b32 s31, s94, s24
	s_ashr_i32 s91, s90, 31
	s_lshl_b64 s[28:29], s[90:91], 19
	s_add_u32 s96, s18, s28
	s_addc_u32 s97, s40, s29
	s_and_b64 s[28:29], s[0:1], exec
	s_cselect_b32 s34, s97, s27
	s_cselect_b32 s35, s96, s26
	s_add_u32 s24, s24, 0x40080
	s_addc_u32 s25, s25, 0
	s_add_u32 s36, s26, 0x100
	v_mov_b32_e32 v2, 0
	s_addc_u32 s37, s27, 0
	s_mov_b32 s38, -2
	v_mov_b32_e32 v3, v2
	v_mov_b64_e32 v[4:5], v[2:3]
	v_mov_b64_e32 v[6:7], v[2:3]
	v_mov_b64_e32 v[8:9], v[2:3]
	v_mov_b64_e32 v[10:11], v[2:3]
	v_mov_b64_e32 v[12:13], v[2:3]
	v_mov_b64_e32 v[14:15], v[2:3]
	v_mov_b64_e32 v[16:17], v[2:3]
	v_mov_b64_e32 v[18:19], v[2:3]
	v_mov_b64_e32 v[20:21], v[2:3]
	v_mov_b64_e32 v[22:23], v[2:3]
	v_mov_b64_e32 v[24:25], v[2:3]
	v_mov_b64_e32 v[26:27], v[2:3]
	v_mov_b64_e32 v[28:29], v[2:3]
	v_mov_b64_e32 v[30:31], v[2:3]
	v_mov_b64_e32 v[32:33], v[2:3]
	v_mov_b64_e32 v[34:35], v[2:3]
	v_mov_b64_e32 v[36:37], v[2:3]
	v_mov_b64_e32 v[38:39], v[2:3]
	v_mov_b64_e32 v[40:41], v[2:3]
	v_mov_b64_e32 v[42:43], v[2:3]
	v_mov_b64_e32 v[44:45], v[2:3]
	v_mov_b64_e32 v[46:47], v[2:3]
	v_mov_b64_e32 v[48:49], v[2:3]
	v_mov_b64_e32 v[50:51], v[2:3]
	v_mov_b64_e32 v[52:53], v[2:3]
	v_mov_b64_e32 v[54:55], v[2:3]
	v_mov_b64_e32 v[56:57], v[2:3]
	v_mov_b64_e32 v[58:59], v[2:3]
	v_mov_b64_e32 v[60:61], v[2:3]
	v_mov_b64_e32 v[62:63], v[2:3]
	v_mov_b64_e32 v[64:65], v[2:3]
	v_mov_b64_e32 v[66:67], v[2:3]
	v_mov_b64_e32 v[68:69], v[2:3]
	v_mov_b64_e32 v[70:71], v[2:3]
	v_mov_b64_e32 v[72:73], v[2:3]
	v_mov_b64_e32 v[74:75], v[2:3]
	v_mov_b64_e32 v[76:77], v[2:3]
	v_mov_b64_e32 v[78:79], v[2:3]
	v_mov_b64_e32 v[80:81], v[2:3]
	v_mov_b64_e32 v[82:83], v[2:3]
	v_mov_b64_e32 v[84:85], v[2:3]
	v_mov_b64_e32 v[86:87], v[2:3]
	v_mov_b64_e32 v[88:89], v[2:3]
	v_mov_b64_e32 v[90:91], v[2:3]
	v_mov_b64_e32 v[92:93], v[2:3]
	v_mov_b64_e32 v[94:95], v[2:3]
	v_mov_b64_e32 v[96:97], v[2:3]
	v_mov_b64_e32 v[98:99], v[2:3]
	v_mov_b64_e32 v[100:101], v[2:3]
	v_mov_b64_e32 v[102:103], v[2:3]
	v_mov_b64_e32 v[104:105], v[2:3]
	v_mov_b64_e32 v[106:107], v[2:3]
	v_mov_b64_e32 v[108:109], v[2:3]
	v_mov_b64_e32 v[110:111], v[2:3]
	v_mov_b64_e32 v[112:113], v[2:3]
	v_mov_b64_e32 v[114:115], v[2:3]
	v_mov_b64_e32 v[116:117], v[2:3]
	v_mov_b64_e32 v[118:119], v[2:3]
	v_mov_b64_e32 v[120:121], v[2:3]
	v_mov_b64_e32 v[122:123], v[2:3]
	v_mov_b64_e32 v[124:125], v[2:3]
	v_mov_b64_e32 v[126:127], v[2:3]
	v_mov_b64_e32 v[128:129], v[2:3]
	.p2alignl 6, 3212836864

; template <class Epi, class Sched, bool ALIGN_EPI = false, bool SP2 = false>
; __device__ __forceinline__ void gemm_phase(PG8_LAS unsigned char* lds, const Gemm g, const Sched& S, const Epi& E, int wave_s) {
;     ...
;         const bool has_next = S.next(ui + 1, nxt);
;         const char* nA = has_next ? (const char*)g.A + (size_t)nxt.pm * tstep : cA; const char* nB = has_next ? (const char*)g.Bt + (size_t)nxt.pn * tstep : cB;
;         for (int t = 0; t < nt; t += 2) {
;             const bool last = (t == nt - 2);
;             const char* a1 = cA + (size_t)(t + 1) * kstep;
;             const char* a2 = last ? nA : cA + (size_t)(t + 2) * kstep; const char* b2 = last ? nB : cB + (size_t)(t + 2) * kstep;
;             const char* a3 = a2 + kstep; const char* b3 = b2 + kstep;
;     ...
; #pragma unroll
;         for (int a = 0; a < 2; ++a)
; #pragma unroll
;             for (int b = 0; b < 2; ++b)
; #pragma unroll
;                 for (int m = 0; m < 4; ++m)
; #pragma unroll
;                     for (int n = 0; n < 2; ++n) acc[a][b][m][n] = (f32x4){0.f, 0.f, 0.f, 0.f};
.LBB0_286:
	s_ashr_i32 s73, s72, 31
	s_lshl_b64 s[26:27], s[72:73], 19
	s_add_u32 s96, s41, s26
	s_addc_u32 s97, s42, s27
	s_and_b64 s[26:27], s[0:1], exec
	s_cselect_b32 s13, s97, s25
	s_cselect_b32 s23, s96, s24
	s_ashr_i32 s93, s92, 31
	s_lshl_b64 s[26:27], s[92:93], 19
	s_add_u32 s58, s43, s26
	s_addc_u32 s59, s44, s27
	s_and_b64 s[26:27], s[0:1], exec
	s_cselect_b32 s30, s59, s7
	s_cselect_b32 s31, s58, s6
	s_add_u32 s24, s24, 0x40080
	s_addc_u32 s25, s25, 0
	s_add_u32 s34, s6, 0x100
	v_mov_b32_e32 v2, 0
	s_addc_u32 s35, s7, 0
	s_mov_b32 s36, -2
	v_mov_b32_e32 v3, v2
	v_mov_b64_e32 v[4:5], v[2:3]
	v_mov_b64_e32 v[6:7], v[2:3]
	v_mov_b64_e32 v[8:9], v[2:3]
	v_mov_b64_e32 v[10:11], v[2:3]
	v_mov_b64_e32 v[12:13], v[2:3]
	v_mov_b64_e32 v[14:15], v[2:3]
	v_mov_b64_e32 v[16:17], v[2:3]
	v_mov_b64_e32 v[18:19], v[2:3]
	v_mov_b64_e32 v[20:21], v[2:3]
	v_mov_b64_e32 v[22:23], v[2:3]
	v_mov_b64_e32 v[24:25], v[2:3]
	v_mov_b64_e32 v[26:27], v[2:3]
	v_mov_b64_e32 v[28:29], v[2:3]
	v_mov_b64_e32 v[30:31], v[2:3]
	v_mov_b64_e32 v[32:33], v[2:3]
	v_mov_b64_e32 v[34:35], v[2:3]
	v_mov_b64_e32 v[36:37], v[2:3]
	v_mov_b64_e32 v[38:39], v[2:3]
	v_mov_b64_e32 v[40:41], v[2:3]
	v_mov_b64_e32 v[42:43], v[2:3]
	v_mov_b64_e32 v[44:45], v[2:3]
	v_mov_b64_e32 v[46:47], v[2:3]
	v_mov_b64_e32 v[48:49], v[2:3]
	v_mov_b64_e32 v[50:51], v[2:3]
	v_mov_b64_e32 v[52:53], v[2:3]
	v_mov_b64_e32 v[54:55], v[2:3]
	v_mov_b64_e32 v[56:57], v[2:3]
	v_mov_b64_e32 v[58:59], v[2:3]
	v_mov_b64_e32 v[60:61], v[2:3]
	v_mov_b64_e32 v[62:63], v[2:3]
	v_mov_b64_e32 v[64:65], v[2:3]
	v_mov_b64_e32 v[66:67], v[2:3]
	v_mov_b64_e32 v[68:69], v[2:3]
	v_mov_b64_e32 v[70:71], v[2:3]
	v_mov_b64_e32 v[72:73], v[2:3]
	v_mov_b64_e32 v[74:75], v[2:3]
	v_mov_b64_e32 v[76:77], v[2:3]
	v_mov_b64_e32 v[78:79], v[2:3]
	v_mov_b64_e32 v[80:81], v[2:3]
	v_mov_b64_e32 v[82:83], v[2:3]
	v_mov_b64_e32 v[84:85], v[2:3]
	v_mov_b64_e32 v[86:87], v[2:3]
	v_mov_b64_e32 v[88:89], v[2:3]
	v_mov_b64_e32 v[90:91], v[2:3]
	v_mov_b64_e32 v[92:93], v[2:3]
	v_mov_b64_e32 v[94:95], v[2:3]
	v_mov_b64_e32 v[96:97], v[2:3]
	v_mov_b64_e32 v[98:99], v[2:3]
	v_mov_b64_e32 v[100:101], v[2:3]
	v_mov_b64_e32 v[102:103], v[2:3]
	v_mov_b64_e32 v[104:105], v[2:3]
	v_mov_b64_e32 v[106:107], v[2:3]
	v_mov_b64_e32 v[108:109], v[2:3]
	v_mov_b64_e32 v[110:111], v[2:3]
	v_mov_b64_e32 v[112:113], v[2:3]
	v_mov_b64_e32 v[114:115], v[2:3]
	v_mov_b64_e32 v[116:117], v[2:3]
	v_mov_b64_e32 v[118:119], v[2:3]
	v_mov_b64_e32 v[120:121], v[2:3]
	v_mov_b64_e32 v[122:123], v[2:3]
	v_mov_b64_e32 v[124:125], v[2:3]
	v_mov_b64_e32 v[126:127], v[2:3]
	v_mov_b64_e32 v[128:129], v[2:3]
	.p2alignl 6, 3212836864

; template <class Epi, class Sched, bool ALIGN_EPI = false, bool SP2 = false>
; __device__ __forceinline__ void gemm_phase(PG8_LAS unsigned char* lds, const Gemm g, const Sched& S, const Epi& E, int wave_s) {
;     ...
;         const bool has_next = S.next(ui + 1, nxt);
;         const char* nA = has_next ? (const char*)g.A + (size_t)nxt.pm * tstep : cA; const char* nB = has_next ? (const char*)g.Bt + (size_t)nxt.pn * tstep : cB;
;         for (int t = 0; t < nt; t += 2) {
;             const bool last = (t == nt - 2);
;             const char* a1 = cA + (size_t)(t + 1) * kstep;
;             const char* a2 = last ? nA : cA + (size_t)(t + 2) * kstep; const char* b2 = last ? nB : cB + (size_t)(t + 2) * kstep;
;             const char* a3 = a2 + kstep; const char* b3 = b2 + kstep;
;     ...
; #pragma unroll
;         for (int a = 0; a < 2; ++a)
; #pragma unroll
;             for (int b = 0; b < 2; ++b)
; #pragma unroll
;                 for (int m = 0; m < 4; ++m)
; #pragma unroll
;                     for (int n = 0; n < 2; ++n) acc[a][b][m][n] = (f32x4){0.f, 0.f, 0.f, 0.f};
.LBB0_318:
	s_ashr_i32 s89, s88, 31
	s_lshl_b64 s[28:29], s[88:89], 19
	s_add_u32 s90, s41, s28
	s_addc_u32 s91, s42, s29
	s_and_b64 s[28:29], s[0:1], exec
	s_cselect_b32 s10, s91, s25
	s_cselect_b32 s31, s90, s24
	s_ashr_i32 s59, s58, 31
	s_lshl_b64 s[28:29], s[58:59], 19
	s_add_u32 s92, s43, s28
	s_addc_u32 s93, s44, s29
	s_and_b64 s[28:29], s[0:1], exec
	s_cselect_b32 s34, s93, s27
	s_cselect_b32 s35, s92, s26
	s_add_u32 s24, s24, 0x40080
	s_addc_u32 s25, s25, 0
	s_add_u32 s36, s26, 0x100
	v_mov_b32_e32 v2, 0
	s_addc_u32 s37, s27, 0
	s_mov_b32 s38, -2
	v_mov_b32_e32 v3, v2
	v_mov_b64_e32 v[4:5], v[2:3]
	v_mov_b64_e32 v[6:7], v[2:3]
	v_mov_b64_e32 v[8:9], v[2:3]
	v_mov_b64_e32 v[10:11], v[2:3]
	v_mov_b64_e32 v[12:13], v[2:3]
	v_mov_b64_e32 v[14:15], v[2:3]
	v_mov_b64_e32 v[16:17], v[2:3]
	v_mov_b64_e32 v[18:19], v[2:3]
	v_mov_b64_e32 v[20:21], v[2:3]
	v_mov_b64_e32 v[22:23], v[2:3]
	v_mov_b64_e32 v[24:25], v[2:3]
	v_mov_b64_e32 v[26:27], v[2:3]
	v_mov_b64_e32 v[28:29], v[2:3]
	v_mov_b64_e32 v[30:31], v[2:3]
	v_mov_b64_e32 v[32:33], v[2:3]
	v_mov_b64_e32 v[34:35], v[2:3]
	v_mov_b64_e32 v[36:37], v[2:3]
	v_mov_b64_e32 v[38:39], v[2:3]
	v_mov_b64_e32 v[40:41], v[2:3]
	v_mov_b64_e32 v[42:43], v[2:3]
	v_mov_b64_e32 v[44:45], v[2:3]
	v_mov_b64_e32 v[46:47], v[2:3]
	v_mov_b64_e32 v[48:49], v[2:3]
	v_mov_b64_e32 v[50:51], v[2:3]
	v_mov_b64_e32 v[52:53], v[2:3]
	v_mov_b64_e32 v[54:55], v[2:3]
	v_mov_b64_e32 v[56:57], v[2:3]
	v_mov_b64_e32 v[58:59], v[2:3]
	v_mov_b64_e32 v[60:61], v[2:3]
	v_mov_b64_e32 v[62:63], v[2:3]
	v_mov_b64_e32 v[64:65], v[2:3]
	v_mov_b64_e32 v[66:67], v[2:3]
	v_mov_b64_e32 v[68:69], v[2:3]
	v_mov_b64_e32 v[70:71], v[2:3]
	v_mov_b64_e32 v[72:73], v[2:3]
	v_mov_b64_e32 v[74:75], v[2:3]
	v_mov_b64_e32 v[76:77], v[2:3]
	v_mov_b64_e32 v[78:79], v[2:3]
	v_mov_b64_e32 v[80:81], v[2:3]
	v_mov_b64_e32 v[82:83], v[2:3]
	v_mov_b64_e32 v[84:85], v[2:3]
	v_mov_b64_e32 v[86:87], v[2:3]
	v_mov_b64_e32 v[88:89], v[2:3]
	v_mov_b64_e32 v[90:91], v[2:3]
	v_mov_b64_e32 v[92:93], v[2:3]
	v_mov_b64_e32 v[94:95], v[2:3]
	v_mov_b64_e32 v[96:97], v[2:3]
	v_mov_b64_e32 v[98:99], v[2:3]
	v_mov_b64_e32 v[100:101], v[2:3]
	v_mov_b64_e32 v[102:103], v[2:3]
	v_mov_b64_e32 v[104:105], v[2:3]
	v_mov_b64_e32 v[106:107], v[2:3]
	v_mov_b64_e32 v[108:109], v[2:3]
	v_mov_b64_e32 v[110:111], v[2:3]
	v_mov_b64_e32 v[112:113], v[2:3]
	v_mov_b64_e32 v[114:115], v[2:3]
	v_mov_b64_e32 v[116:117], v[2:3]
	v_mov_b64_e32 v[118:119], v[2:3]
	v_mov_b64_e32 v[120:121], v[2:3]
	v_mov_b64_e32 v[122:123], v[2:3]
	v_mov_b64_e32 v[124:125], v[2:3]
	v_mov_b64_e32 v[126:127], v[2:3]
	v_mov_b64_e32 v[128:129], v[2:3]
	.p2alignl 6, 3212836864

.LBB0_566:
	v_exp_f32_e32 v0, v80
	v_exp_f32_e32 v2, v96
	v_exp_f32_e32 v3, v81
	v_exp_f32_e32 v4, v97
	v_add_f32_e32 v5, 0, v0
	v_exp_f32_e32 v6, v82
	v_add_f32_e32 v5, v2, v5
	v_exp_f32_e32 v7, v98
	v_add_f32_e32 v5, v5, v3
	v_exp_f32_e32 v8, v83
	v_add_f32_e32 v5, v4, v5
	v_exp_f32_e32 v9, v99
	v_add_f32_e32 v5, v6, v5
	v_exp_f32_e32 v10, v84
	v_add_f32_e32 v5, v7, v5
	v_exp_f32_e32 v11, v100
	v_add_f32_e32 v5, v8, v5
	v_exp_f32_e32 v12, v85
	v_add_f32_e32 v5, v9, v5
	v_exp_f32_e32 v13, v101
	v_add_f32_e32 v5, v10, v5
	v_exp_f32_e32 v14, v86
	v_add_f32_e32 v5, v11, v5
	v_exp_f32_e32 v15, v102
	v_add_f32_e32 v5, v12, v5
	v_exp_f32_e32 v83, v87
	v_add_f32_e32 v5, v13, v5
	v_exp_f32_e32 v96, v103
	v_add_f32_e32 v5, v14, v5
	v_exp_f32_e32 v84, v88
	v_add_f32_e32 v5, v15, v5
	v_exp_f32_e32 v97, v104
	v_add_f32_e32 v5, v83, v5
	v_exp_f32_e32 v85, v89
	v_add_f32_e32 v5, v96, v5
	v_exp_f32_e32 v98, v105
	v_add_f32_e32 v5, v84, v5
	v_exp_f32_e32 v86, v90
	v_add_f32_e32 v5, v97, v5
	v_exp_f32_e32 v99, v106
	v_add_f32_e32 v5, v85, v5
	v_exp_f32_e32 v87, v91
	v_add_f32_e32 v5, v98, v5
	v_exp_f32_e32 v100, v107
	v_add_f32_e32 v5, v86, v5
	v_exp_f32_e32 v88, v92
	v_add_f32_e32 v5, v99, v5
	v_exp_f32_e32 v101, v108
	v_add_f32_e32 v5, v87, v5
	v_exp_f32_e32 v89, v93
	v_add_f32_e32 v5, v100, v5
	v_exp_f32_e32 v102, v109
	v_add_f32_e32 v5, v88, v5
	v_exp_f32_e32 v90, v94
	v_add_f32_e32 v5, v101, v5
	v_exp_f32_e32 v103, v110
	v_add_f32_e32 v5, v89, v5
	v_exp_f32_e32 v91, v95
	v_add_f32_e32 v5, v102, v5
	v_exp_f32_e32 v95, v111
	v_add_f32_e32 v5, v90, v5
	s_add_i32 s10, s10, 64
	v_add_f32_e32 v5, v103, v5
	s_add_i32 s12, s12, 1
	v_add_f32_e32 v5, v91, v5
	v_cvt_pk_bf16_f32 v80, v0, v3
	v_add_f32_e32 v5, v95, v5
	v_cvt_pk_bf16_f32 v81, v6, v8
	v_add_f32_e32 v194, v194, v5
	v_cvt_pk_bf16_f32 v82, v10, v12
	v_cvt_pk_bf16_f32 v83, v14, v83
	v_cvt_pk_bf16_f32 v84, v84, v85
	v_cvt_pk_bf16_f32 v85, v86, v87
	v_cvt_pk_bf16_f32 v86, v88, v89
	v_cvt_pk_bf16_f32 v87, v90, v91
	v_cvt_pk_bf16_f32 v88, v2, v4
	v_cvt_pk_bf16_f32 v89, v7, v9
	v_cvt_pk_bf16_f32 v90, v11, v13
	v_cvt_pk_bf16_f32 v91, v15, v96
	v_cvt_pk_bf16_f32 v92, v97, v98
	v_cvt_pk_bf16_f32 v93, v99, v100
	v_cvt_pk_bf16_f32 v94, v101, v102
	s_cmp_ge_i32 s13, s42
	v_cvt_pk_bf16_f32 v95, v103, v95
	s_cbranch_scc1 .LBB0_584
	.p2alignl 6, 3212836864

; #define C3_BAR() asm volatile("s_waitcnt lgkmcnt(0)\n\ts_barrier" ::: "memory")
; __device__ __forceinline__ void attn_C5(const Ctx& a, LAS unsigned char* lds, int wave_s) {
;     ...
;         } else {
;             int vs = 0;
;             for (int t = t_lo; t < TE; ++t) {
;                 C3_BAR();
;                 if (t > t_lo) { const int vsp = vs == 0 ? 2 : vs - 1; C3_PV(vsp); } C3_QK(t);
.LBB0_608:
	s_and_b64 vcc, exec, s[4:5]
	s_cbranch_vccnz .LBB0_628
	s_lshl_b32 s2, s43, 6
	s_add_i32 s10, s2, 0xc0
	s_mov_b32 s13, 1
	.p2alignl 6, 3212836864

; template <class Epi, class Sched, bool ALIGN_EPI = false, bool SP2 = false>
; __device__ __forceinline__ void gemm_phase(PG8_LAS unsigned char* lds, const Gemm g, const Sched& S, const Epi& E, int wave_s) {
;     ...
;         const bool has_next = S.next(ui + 1, nxt);
;         const char* nA = has_next ? (const char*)g.A + (size_t)nxt.pm * tstep : cA; const char* nB = has_next ? (const char*)g.Bt + (size_t)nxt.pn * tstep : cB;
;         for (int t = 0; t < nt; t += 2) {
;             const bool last = (t == nt - 2);
;             const char* a1 = cA + (size_t)(t + 1) * kstep;
;             const char* a2 = last ? nA : cA + (size_t)(t + 2) * kstep; const char* b2 = last ? nB : cB + (size_t)(t + 2) * kstep;
;             const char* a3 = a2 + kstep; const char* b3 = b2 + kstep;
;     ...
; #pragma unroll
;         for (int a = 0; a < 2; ++a)
; #pragma unroll
;             for (int b = 0; b < 2; ++b)
; #pragma unroll
;                 for (int m = 0; m < 4; ++m)
; #pragma unroll
;                     for (int n = 0; n < 2; ++n) acc[a][b][m][n] = (f32x4){0.f, 0.f, 0.f, 0.f};
.LBB0_742:
	s_ashr_i32 s89, s88, 31
	s_lshl_b64 s[28:29], s[88:89], s23
	s_add_u32 s90, s12, s28
	s_addc_u32 s91, s13, s29
	s_and_b64 s[28:29], s[0:1], exec
	s_cselect_b32 s28, s91, s25
	s_cselect_b32 s29, s90, s24
	s_ashr_i32 s73, s72, 31
	s_lshl_b64 s[70:71], s[72:73], s23
	s_add_u32 s92, s16, s70
	s_addc_u32 s93, s18, s71
	s_and_b64 s[70:71], s[0:1], exec
	s_cselect_b32 s45, s93, s27
	s_cselect_b32 s51, s92, s26
	s_add_u32 s24, s24, 0x80
	s_addc_u32 s25, s25, 0
	s_add_u32 s57, s26, 0x100
	v_mov_b32_e32 v2, 0
	s_addc_u32 s63, s27, 0
	s_mov_b32 s26, 0
	v_mov_b32_e32 v3, v2
	v_mov_b64_e32 v[4:5], v[2:3]
	v_mov_b64_e32 v[6:7], v[2:3]
	v_mov_b64_e32 v[8:9], v[2:3]
	v_mov_b64_e32 v[10:11], v[2:3]
	v_mov_b64_e32 v[12:13], v[2:3]
	v_mov_b64_e32 v[14:15], v[2:3]
	v_mov_b64_e32 v[16:17], v[2:3]
	v_mov_b64_e32 v[18:19], v[2:3]
	v_mov_b64_e32 v[20:21], v[2:3]
	v_mov_b64_e32 v[22:23], v[2:3]
	v_mov_b64_e32 v[24:25], v[2:3]
	v_mov_b64_e32 v[26:27], v[2:3]
	v_mov_b64_e32 v[28:29], v[2:3]
	v_mov_b64_e32 v[30:31], v[2:3]
	v_mov_b64_e32 v[32:33], v[2:3]
	v_mov_b64_e32 v[34:35], v[2:3]
	v_mov_b64_e32 v[36:37], v[2:3]
	v_mov_b64_e32 v[38:39], v[2:3]
	v_mov_b64_e32 v[40:41], v[2:3]
	v_mov_b64_e32 v[42:43], v[2:3]
	v_mov_b64_e32 v[44:45], v[2:3]
	v_mov_b64_e32 v[46:47], v[2:3]
	v_mov_b64_e32 v[48:49], v[2:3]
	v_mov_b64_e32 v[50:51], v[2:3]
	v_mov_b64_e32 v[52:53], v[2:3]
	v_mov_b64_e32 v[54:55], v[2:3]
	v_mov_b64_e32 v[56:57], v[2:3]
	v_mov_b64_e32 v[58:59], v[2:3]
	v_mov_b64_e32 v[60:61], v[2:3]
	v_mov_b64_e32 v[62:63], v[2:3]
	v_mov_b64_e32 v[64:65], v[2:3]
	v_mov_b64_e32 v[66:67], v[2:3]
	v_mov_b64_e32 v[68:69], v[2:3]
	v_mov_b64_e32 v[70:71], v[2:3]
	v_mov_b64_e32 v[72:73], v[2:3]
	v_mov_b64_e32 v[74:75], v[2:3]
	v_mov_b64_e32 v[76:77], v[2:3]
	v_mov_b64_e32 v[78:79], v[2:3]
	v_mov_b64_e32 v[80:81], v[2:3]
	v_mov_b64_e32 v[82:83], v[2:3]
	v_mov_b64_e32 v[84:85], v[2:3]
	v_mov_b64_e32 v[86:87], v[2:3]
	v_mov_b64_e32 v[88:89], v[2:3]
	v_mov_b64_e32 v[90:91], v[2:3]
	v_mov_b64_e32 v[92:93], v[2:3]
	v_mov_b64_e32 v[94:95], v[2:3]
	v_mov_b64_e32 v[96:97], v[2:3]
	v_mov_b64_e32 v[98:99], v[2:3]
	v_mov_b64_e32 v[100:101], v[2:3]
	v_mov_b64_e32 v[102:103], v[2:3]
	v_mov_b64_e32 v[104:105], v[2:3]
	v_mov_b64_e32 v[106:107], v[2:3]
	v_mov_b64_e32 v[108:109], v[2:3]
	v_mov_b64_e32 v[110:111], v[2:3]
	v_mov_b64_e32 v[112:113], v[2:3]
	v_mov_b64_e32 v[114:115], v[2:3]
	v_mov_b64_e32 v[116:117], v[2:3]
	v_mov_b64_e32 v[118:119], v[2:3]
	v_mov_b64_e32 v[120:121], v[2:3]
	v_mov_b64_e32 v[122:123], v[2:3]
	v_mov_b64_e32 v[124:125], v[2:3]
	v_mov_b64_e32 v[126:127], v[2:3]
	v_mov_b64_e32 v[128:129], v[2:3]
	.p2alignl 6, 3212836864

; template <class Epi, class Sched, bool ALIGN_EPI = false, bool SP2 = false>
; __device__ __forceinline__ void gemm_phase(PG8_LAS unsigned char* lds, const Gemm g, const Sched& S, const Epi& E, int wave_s) {
;     ...
;         const bool has_next = S.next(ui + 1, nxt);
;         const char* nA = has_next ? (const char*)g.A + (size_t)nxt.pm * tstep : cA; const char* nB = has_next ? (const char*)g.Bt + (size_t)nxt.pn * tstep : cB;
;         for (int t = 0; t < nt; t += 2) {
;             const bool last = (t == nt - 2);
;             const char* a1 = cA + (size_t)(t + 1) * kstep;
;             const char* a2 = last ? nA : cA + (size_t)(t + 2) * kstep; const char* b2 = last ? nB : cB + (size_t)(t + 2) * kstep;
;             const char* a3 = a2 + kstep; const char* b3 = b2 + kstep;
;     ...
; #pragma unroll
;         for (int a = 0; a < 2; ++a)
; #pragma unroll
;             for (int b = 0; b < 2; ++b)
; #pragma unroll
;                 for (int m = 0; m < 4; ++m)
; #pragma unroll
;                     for (int n = 0; n < 2; ++n) acc[a][b][m][n] = (f32x4){0.f, 0.f, 0.f, 0.f};
.LBB0_917:
	s_ashr_i32 s89, s88, 31
	s_lshl_b64 s[28:29], s[88:89], 19
	s_add_u32 s90, s12, s28
	s_addc_u32 s91, s13, s29
	s_and_b64 s[28:29], s[0:1], exec
	s_cselect_b32 s41, s91, s25
	s_cselect_b32 s42, s90, s24
	s_ashr_i32 s87, s86, 31
	s_lshl_b64 s[28:29], s[86:87], 19
	s_add_u32 s92, s16, s28
	s_addc_u32 s93, s18, s29
	s_and_b64 s[28:29], s[0:1], exec
	s_cselect_b32 s43, s93, s27
	s_cselect_b32 s44, s92, s26
	s_add_u32 s24, s24, 0x40080
	s_addc_u32 s25, s25, 0
	s_add_u32 s45, s26, 0x100
	v_mov_b32_e32 v2, 0
	s_addc_u32 s51, s27, 0
	s_mov_b32 s57, -2
	v_mov_b32_e32 v3, v2
	v_mov_b64_e32 v[4:5], v[2:3]
	v_mov_b64_e32 v[6:7], v[2:3]
	v_mov_b64_e32 v[8:9], v[2:3]
	v_mov_b64_e32 v[10:11], v[2:3]
	v_mov_b64_e32 v[12:13], v[2:3]
	v_mov_b64_e32 v[14:15], v[2:3]
	v_mov_b64_e32 v[16:17], v[2:3]
	v_mov_b64_e32 v[18:19], v[2:3]
	v_mov_b64_e32 v[20:21], v[2:3]
	v_mov_b64_e32 v[22:23], v[2:3]
	v_mov_b64_e32 v[24:25], v[2:3]
	v_mov_b64_e32 v[26:27], v[2:3]
	v_mov_b64_e32 v[28:29], v[2:3]
	v_mov_b64_e32 v[30:31], v[2:3]
	v_mov_b64_e32 v[32:33], v[2:3]
	v_mov_b64_e32 v[34:35], v[2:3]
	v_mov_b64_e32 v[36:37], v[2:3]
	v_mov_b64_e32 v[38:39], v[2:3]
	v_mov_b64_e32 v[40:41], v[2:3]
	v_mov_b64_e32 v[42:43], v[2:3]
	v_mov_b64_e32 v[44:45], v[2:3]
	v_mov_b64_e32 v[46:47], v[2:3]
	v_mov_b64_e32 v[48:49], v[2:3]
	v_mov_b64_e32 v[50:51], v[2:3]
	v_mov_b64_e32 v[52:53], v[2:3]
	v_mov_b64_e32 v[54:55], v[2:3]
	v_mov_b64_e32 v[56:57], v[2:3]
	v_mov_b64_e32 v[58:59], v[2:3]
	v_mov_b64_e32 v[60:61], v[2:3]
	v_mov_b64_e32 v[62:63], v[2:3]
	v_mov_b64_e32 v[64:65], v[2:3]
	v_mov_b64_e32 v[66:67], v[2:3]
	v_mov_b64_e32 v[68:69], v[2:3]
	v_mov_b64_e32 v[70:71], v[2:3]
	v_mov_b64_e32 v[72:73], v[2:3]
	v_mov_b64_e32 v[74:75], v[2:3]
	v_mov_b64_e32 v[76:77], v[2:3]
	v_mov_b64_e32 v[78:79], v[2:3]
	v_mov_b64_e32 v[80:81], v[2:3]
	v_mov_b64_e32 v[82:83], v[2:3]
	v_mov_b64_e32 v[84:85], v[2:3]
	v_mov_b64_e32 v[86:87], v[2:3]
	v_mov_b64_e32 v[88:89], v[2:3]
	v_mov_b64_e32 v[90:91], v[2:3]
	v_mov_b64_e32 v[92:93], v[2:3]
	v_mov_b64_e32 v[94:95], v[2:3]
	v_mov_b64_e32 v[96:97], v[2:3]
	v_mov_b64_e32 v[98:99], v[2:3]
	v_mov_b64_e32 v[100:101], v[2:3]
	v_mov_b64_e32 v[102:103], v[2:3]
	v_mov_b64_e32 v[104:105], v[2:3]
	v_mov_b64_e32 v[106:107], v[2:3]
	v_mov_b64_e32 v[108:109], v[2:3]
	v_mov_b64_e32 v[110:111], v[2:3]
	v_mov_b64_e32 v[112:113], v[2:3]
	v_mov_b64_e32 v[114:115], v[2:3]
	v_mov_b64_e32 v[116:117], v[2:3]
	v_mov_b64_e32 v[118:119], v[2:3]
	v_mov_b64_e32 v[120:121], v[2:3]
	v_mov_b64_e32 v[122:123], v[2:3]
	v_mov_b64_e32 v[124:125], v[2:3]
	v_mov_b64_e32 v[126:127], v[2:3]
	v_mov_b64_e32 v[128:129], v[2:3]
	.p2alignl 6, 3212836864

; template <class Epi, class Sched, bool ALIGN_EPI = false, bool SP2 = false>
; __device__ __forceinline__ void gemm_phase(PG8_LAS unsigned char* lds, const Gemm g, const Sched& S, const Epi& E, int wave_s) {
;     ...
;         const bool has_next = S.next(ui + 1, nxt);
;         const char* nA = has_next ? (const char*)g.A + (size_t)nxt.pm * tstep : cA; const char* nB = has_next ? (const char*)g.Bt + (size_t)nxt.pn * tstep : cB;
;         for (int t = 0; t < nt; t += 2) {
;             const bool last = (t == nt - 2);
;             const char* a1 = cA + (size_t)(t + 1) * kstep;
;             const char* a2 = last ? nA : cA + (size_t)(t + 2) * kstep; const char* b2 = last ? nB : cB + (size_t)(t + 2) * kstep;
;             const char* a3 = a2 + kstep; const char* b3 = b2 + kstep;
;     ...
; #pragma unroll
;         for (int a = 0; a < 2; ++a)
; #pragma unroll
;             for (int b = 0; b < 2; ++b)
; #pragma unroll
;                 for (int m = 0; m < 4; ++m)
; #pragma unroll
;                     for (int n = 0; n < 2; ++n) acc[a][b][m][n] = (f32x4){0.f, 0.f, 0.f, 0.f};
.LBB0_985:
	s_ashr_i32 s87, s86, 31
	s_lshl_b64 s[28:29], s[86:87], 21
	s_add_u32 s88, s10, s28
	s_addc_u32 s89, s12, s29
	s_and_b64 s[28:29], s[0:1], exec
	s_cselect_b32 s41, s89, s25
	s_cselect_b32 s42, s88, s24
	s_ashr_i32 s73, s72, 31
	s_lshl_b64 s[28:29], s[72:73], 21
	s_add_u32 s90, s13, s28
	s_addc_u32 s91, s16, s29
	s_and_b64 s[28:29], s[0:1], exec
	s_cselect_b32 s43, s91, s27
	s_cselect_b32 s44, s90, s26
	s_add_u32 s24, s24, 0x100080
	s_addc_u32 s25, s25, 0
	s_add_u32 s45, s26, 0x100
	v_mov_b32_e32 v2, 0
	s_addc_u32 s51, s27, 0
	s_mov_b32 s57, -2
	v_mov_b32_e32 v3, v2
	v_mov_b64_e32 v[4:5], v[2:3]
	v_mov_b64_e32 v[6:7], v[2:3]
	v_mov_b64_e32 v[8:9], v[2:3]
	v_mov_b64_e32 v[10:11], v[2:3]
	v_mov_b64_e32 v[12:13], v[2:3]
	v_mov_b64_e32 v[14:15], v[2:3]
	v_mov_b64_e32 v[16:17], v[2:3]
	v_mov_b64_e32 v[18:19], v[2:3]
	v_mov_b64_e32 v[20:21], v[2:3]
	v_mov_b64_e32 v[22:23], v[2:3]
	v_mov_b64_e32 v[24:25], v[2:3]
	v_mov_b64_e32 v[26:27], v[2:3]
	v_mov_b64_e32 v[28:29], v[2:3]
	v_mov_b64_e32 v[30:31], v[2:3]
	v_mov_b64_e32 v[32:33], v[2:3]
	v_mov_b64_e32 v[34:35], v[2:3]
	v_mov_b64_e32 v[36:37], v[2:3]
	v_mov_b64_e32 v[38:39], v[2:3]
	v_mov_b64_e32 v[40:41], v[2:3]
	v_mov_b64_e32 v[42:43], v[2:3]
	v_mov_b64_e32 v[44:45], v[2:3]
	v_mov_b64_e32 v[46:47], v[2:3]
	v_mov_b64_e32 v[48:49], v[2:3]
	v_mov_b64_e32 v[50:51], v[2:3]
	v_mov_b64_e32 v[52:53], v[2:3]
	v_mov_b64_e32 v[54:55], v[2:3]
	v_mov_b64_e32 v[56:57], v[2:3]
	v_mov_b64_e32 v[58:59], v[2:3]
	v_mov_b64_e32 v[60:61], v[2:3]
	v_mov_b64_e32 v[62:63], v[2:3]
	v_mov_b64_e32 v[64:65], v[2:3]
	v_mov_b64_e32 v[66:67], v[2:3]
	v_mov_b64_e32 v[68:69], v[2:3]
	v_mov_b64_e32 v[70:71], v[2:3]
	v_mov_b64_e32 v[72:73], v[2:3]
	v_mov_b64_e32 v[74:75], v[2:3]
	v_mov_b64_e32 v[76:77], v[2:3]
	v_mov_b64_e32 v[78:79], v[2:3]
	v_mov_b64_e32 v[80:81], v[2:3]
	v_mov_b64_e32 v[82:83], v[2:3]
	v_mov_b64_e32 v[84:85], v[2:3]
	v_mov_b64_e32 v[86:87], v[2:3]
	v_mov_b64_e32 v[88:89], v[2:3]
	v_mov_b64_e32 v[90:91], v[2:3]
	v_mov_b64_e32 v[92:93], v[2:3]
	v_mov_b64_e32 v[94:95], v[2:3]
	v_mov_b64_e32 v[96:97], v[2:3]
	v_mov_b64_e32 v[98:99], v[2:3]
	v_mov_b64_e32 v[100:101], v[2:3]
	v_mov_b64_e32 v[102:103], v[2:3]
	v_mov_b64_e32 v[104:105], v[2:3]
	v_mov_b64_e32 v[106:107], v[2:3]
	v_mov_b64_e32 v[108:109], v[2:3]
	v_mov_b64_e32 v[110:111], v[2:3]
	v_mov_b64_e32 v[112:113], v[2:3]
	v_mov_b64_e32 v[114:115], v[2:3]
	v_mov_b64_e32 v[116:117], v[2:3]
	v_mov_b64_e32 v[118:119], v[2:3]
	v_mov_b64_e32 v[120:121], v[2:3]
	v_mov_b64_e32 v[122:123], v[2:3]
	v_mov_b64_e32 v[124:125], v[2:3]
	v_mov_b64_e32 v[126:127], v[2:3]
	v_mov_b64_e32 v[128:129], v[2:3]
	.p2alignl 6, 3212836864
